# v095 + rwkv_p3 and attn_finalize made batch-local: every grid barrier after the prep phase except layer 1's k3->k4 is XCD-local (14 of 16)
# speedup vs baseline: 1.0368x; 1.0084x over previous
;     __device__ __forceinline__ unsigned char* ws() const { return *(const __attribute__((address_space(4))) ucptr_t*)(p + 264); }
; __device__ __forceinline__ void rwkv_p3(const KA& A, const Ctx& F) {
;     ...
;     const int lane = F.lane, w = F.wave, r32 = lane & 31, hh = lane >> 5, tb2 = w & 1;
; #pragma unroll 1
;     for (int it4 = F.bid; it4 < RW_ITEMS / 4; it4 += F.G) {
;         const int item = (RW_ITEMS / 4 - 1 - it4) * 4 + (w >> 1); const int j = item & 63, h = (item >> 6) % 6, b = item / 384;
;         const size_t row0 = (size_t)b * SEQ + 64 * j;
;         const int t = 32 * tb2 + r32;
;         const bf16* qd = PS + (row0 + t) * PSW + C_RW + h * 64; const bf16* yd = qd + 384; const bf16* ed = qd + 768; const bf16* EM = (const bf16*)(F.ws + WS_REM) + (size_t)item * 4096 + t * 64;
;         const bf16* HS = (const bf16*)(F.ws + WS_RHS) + (size_t)item * 4096;
.LBB0_162:
	v_mov_b32_e32 v0, v242
	s_cmpk_gt_i32 s80, 0x2ff
	v_readfirstlane_b32 s0, v0
	s_cbranch_scc1 .LBB0_165
	v_and_b32_e32 v1, 31, v0
	s_ashr_i32 s2, s0, 7
	s_lshr_b32 s0, s0, 1
	v_and_or_b32 v64, s0, 32, v1
	v_readlane_b32 s4, v253, 60
	v_lshrrev_b32_e32 v1, 2, v0
	v_lshlrev_b32_e32 v80, 7, v64
	v_readlane_b32 s6, v253, 62
	v_readlane_b32 s7, v253, 63
	v_lshlrev_b32_e32 v0, 4, v0
	v_and_b32_e32 v2, 8, v1
	v_lshl_add_u64 v[4:5], s[6:7], 0, v[80:81]
	v_and_b32_e32 v80, 0x3f0, v0
	v_lshl_add_u64 v[66:67], s[28:29], 0, v[80:81]
	v_lshlrev_b32_e32 v80, 1, v2
	v_lshl_add_u64 v[0:1], v[4:5], 0, v[80:81]
	s_mov_b64 s[0:1], 0x1d800000
	v_lshl_add_u64 v[68:69], v[0:1], 0, s[0:1]
	s_and_b32 s1, s80, 7
	s_sub_i32 s1, 7, s1
	s_mulk_i32 s1, 0x60
	s_lshr_b32 s0, s80, 3
	s_add_i32 s1, s1, s0
	s_lshl_b32 s0, s1, 2
	s_sub_i32 s0, s2, s0
	v_readlane_b32 s5, v253, 61
	s_addk_i32 s0, 0xbfc
	s_movk_i32 s2, 0x80
	s_lshl_b32 s3, s0, 6
	s_movk_i32 s4, 0x2000
	v_lshlrev_b32_e32 v80, 1, v2
	s_mov_b32 s5, s80

; __device__ __forceinline__ void attn_finalize(const KA& A, const Ctx& F) {
;     ...
; #pragma unroll 1
;     for (int o = 0; o < 2; ++o) {
;         v4u w[6]; float l0[6], l1[6], l2[6]; v4u* p[6];
; #pragma unroll
;         for (int u = 0; u < 6; ++u) { const int item = T * 48 - 1 - ((o * 6 + u) * (F.G * NTHREADS) + F.bid * NTHREADS + F.tid);
;             const int bt = item / 48, r = item % 48, h = r >> 3, c = r & 7, j = h & 1;
;             l0[u] = LSE[(size_t)bt * 6 + j]; l1[u] = LSE[(size_t)bt * 6 + 2 + j]; l2[u] = LSE[(size_t)bt * 6 + 4 + j];
;             p[u] = (v4u*)(PS + (size_t)bt * PSW + C_Q + h * 64) + c; w[u] = *p[u]; }
;         asm volatile("" :: "v"(w[0]), "v"(w[1]), "v"(w[2]), "v"(w[3]), "v"(w[4]), "v"(w[5]), "v"(l0[0]), "v"(l0[1]), "v"(l0[2]), "v"(l0[3]), "v"(l0[4]), "v"(l0[5]));
.LBB0_165:
	v_readlane_b32 s0, v253, 60
	v_readlane_b32 s2, v253, 62
	v_readlane_b32 s1, v253, 61
	v_readlane_b32 s3, v253, 63
	s_add_u32 s0, s2, 0x1a400000
	v_mov_b32_e32 v0, v242
	s_addc_u32 s1, s3, 0
	s_mov_b32 s4, 0
	s_mov_b64 s[2:3], -1
	s_and_b32 s11, s80, 7
	s_sub_i32 s11, 7, s11
	s_mulk_i32 s11, 0x180
	s_lshr_b32 s10, s80, 3
	s_add_i32 s11, s11, s10
	s_movk_i32 s10, 32
.LBB0_166:
	v_cndmask_b32_e64 v1, 0, 1, s[2:3]
	s_mul_i32 s2, s4, s10
	s_sub_i32 s3, s2, s11
	s_lshl_b32 s6, s3, 9
	v_cmp_ne_u32_e32 vcc, 1, v1
	v_sub_u32_e32 v1, s6, v0
	v_add_u32_e32 v1, 0x17ffff, v1
	v_mul_hi_i32 v2, v1, s78
	v_lshrrev_b32_e32 v3, 31, v2
	v_ashrrev_i32_e32 v2, 3, v2
	v_add_u32_e32 v4, v2, v3
	v_mul_lo_u32 v2, v4, 48
	s_mul_i32 s3, s10, 0x7fffff
	v_sub_u32_e32 v1, v1, v2
	s_add_i32 s2, s2, s3
	v_ashrrev_i32_e32 v5, 3, v1
	s_sub_i32 s3, s2, s11
	v_lshlrev_b32_e32 v7, 2, v5
	s_lshl_b32 s8, s3, 9
	v_and_b32_e32 v6, 7, v1
	v_mad_i64_i32 v[2:3], s[6:7], v4, 24, s[0:1]
	v_and_b32_e32 v80, 4, v7
	v_lshl_add_u64 v[2:3], v[2:3], 0, v[80:81]
	v_lshlrev_b32_e32 v80, 4, v6
	v_sub_u32_e32 v6, s8, v0
	v_add_u32_e32 v6, 0x17ffff, v6
	v_mul_hi_i32 v7, v6, s78
	v_lshrrev_b32_e32 v8, 31, v7
	v_ashrrev_i32_e32 v7, 3, v7
	v_add_u32_e32 v8, v7, v8
	s_waitcnt vmcnt(5)
	v_mov_b64_e32 v[22:23], s[82:83]
	v_mul_lo_u32 v7, v8, 48
	global_load_dword v38, v[2:3], off
	global_load_dword v39, v[2:3], off offset:8
	global_load_dword v40, v[2:3], off offset:16
	v_mad_i64_i32 v[2:3], s[6:7], v4, s92, v[22:23]
	v_lshlrev_b32_e32 v4, 6, v5
	v_sub_u32_e32 v42, v6, v7
	s_sub_i32 s2, s2, s10
	v_ashrrev_i32_e32 v5, 31, v4
	v_ashrrev_i32_e32 v9, 3, v42
	s_sub_i32 s3, s2, s11
	v_lshl_add_u64 v[2:3], v[4:5], 1, v[2:3]
	v_lshlrev_b32_e32 v11, 2, v9
	s_lshl_b32 s5, s3, 9
	v_lshl_add_u64 v[26:27], v[2:3], 0, v[80:81]
	v_and_b32_e32 v10, 7, v42
	v_mad_i64_i32 v[6:7], s[6:7], v8, 24, s[0:1]
	v_and_b32_e32 v80, 4, v11
	v_lshl_add_u64 v[6:7], v[6:7], 0, v[80:81]
	v_lshlrev_b32_e32 v80, 4, v10
	v_sub_u32_e32 v10, s5, v0
	v_add_u32_e32 v10, 0x17ffff, v10
	v_mul_hi_i32 v11, v10, s78
	v_lshrrev_b32_e32 v12, 31, v11
	v_ashrrev_i32_e32 v11, 3, v11
	v_add_u32_e32 v12, v11, v12
	v_mul_lo_u32 v11, v12, 48
	global_load_dwordx4 v[2:5], v[26:27], off
	global_load_dword v43, v[6:7], off
	global_load_dword v44, v[6:7], off offset:8
	global_load_dword v45, v[6:7], off offset:16
	v_mad_i64_i32 v[6:7], s[6:7], v8, s92, v[22:23]
	v_lshlrev_b32_e32 v8, 6, v9
	v_sub_u32_e32 v46, v10, v11
	s_sub_i32 s2, s2, s10
	v_ashrrev_i32_e32 v9, 31, v8
	v_ashrrev_i32_e32 v13, 3, v46
	s_sub_i32 s3, s2, s11
	v_lshl_add_u64 v[6:7], v[8:9], 1, v[6:7]
	v_lshlrev_b32_e32 v15, 2, v13
	s_lshl_b32 s4, s3, 9
	v_lshl_add_u64 v[28:29], v[6:7], 0, v[80:81]
	v_and_b32_e32 v14, 7, v46
	v_mad_i64_i32 v[10:11], s[6:7], v12, 24, s[0:1]
	v_and_b32_e32 v80, 4, v15
	v_lshl_add_u64 v[10:11], v[10:11], 0, v[80:81]
	v_lshlrev_b32_e32 v80, 4, v14
	v_sub_u32_e32 v14, s4, v0
	v_add_u32_e32 v14, 0x17ffff, v14
	v_mul_hi_i32 v15, v14, s78
	s_waitcnt vmcnt(11)
	v_lshrrev_b32_e32 v16, 31, v15
	v_ashrrev_i32_e32 v15, 3, v15
	v_add_u32_e32 v16, v15, v16
	v_mul_lo_u32 v15, v16, 48
	global_load_dwordx4 v[6:9], v[28:29], off
	global_load_dword v47, v[10:11], off
	global_load_dword v48, v[10:11], off offset:8
	global_load_dword v49, v[10:11], off offset:16
	v_mad_i64_i32 v[10:11], s[6:7], v12, s92, v[22:23]
	v_lshlrev_b32_e32 v12, 6, v13
	v_sub_u32_e32 v50, v14, v15
	s_sub_i32 s2, s2, s10
	v_ashrrev_i32_e32 v13, 31, v12
	v_ashrrev_i32_e32 v17, 3, v50
	s_sub_i32 s3, s2, s11
	v_lshl_add_u64 v[10:11], v[12:13], 1, v[10:11]
	v_lshlrev_b32_e32 v19, 2, v17
	s_lshl_b32 s3, s3, 9
	v_lshl_add_u64 v[30:31], v[10:11], 0, v[80:81]
	v_and_b32_e32 v18, 7, v50
	v_mad_i64_i32 v[14:15], s[4:5], v16, 24, s[0:1]
	v_and_b32_e32 v80, 4, v19
	v_lshl_add_u64 v[14:15], v[14:15], 0, v[80:81]
	v_lshlrev_b32_e32 v80, 4, v18
	v_sub_u32_e32 v18, s3, v0
	v_add_u32_e32 v18, 0x17ffff, v18
	v_mul_hi_i32 v19, v18, s78
	v_lshrrev_b32_e32 v20, 31, v19
	v_ashrrev_i32_e32 v19, 3, v19
	v_add_u32_e32 v20, v19, v20
	v_mul_lo_u32 v19, v20, 48
	global_load_dwordx4 v[10:13], v[30:31], off
	global_load_dword v51, v[14:15], off
	global_load_dword v52, v[14:15], off offset:8
	global_load_dword v53, v[14:15], off offset:16
	v_mad_i64_i32 v[14:15], s[4:5], v16, s92, v[22:23]
	v_lshlrev_b32_e32 v16, 6, v17
	v_sub_u32_e32 v54, v18, v19
	s_sub_i32 s2, s2, s10
	v_ashrrev_i32_e32 v17, 31, v16
	v_ashrrev_i32_e32 v21, 3, v54
	s_sub_i32 s2, s2, s11
	v_lshl_add_u64 v[14:15], v[16:17], 1, v[14:15]
	v_lshlrev_b32_e32 v25, 2, v21
	s_lshl_b32 s2, s2, 9
	v_lshl_add_u64 v[32:33], v[14:15], 0, v[80:81]
	v_and_b32_e32 v24, 7, v54
	v_mad_i64_i32 v[18:19], s[4:5], v20, 24, s[0:1]
	v_and_b32_e32 v80, 4, v25
	v_lshl_add_u64 v[18:19], v[18:19], 0, v[80:81]
	v_lshlrev_b32_e32 v80, 4, v24
	v_sub_u32_e32 v24, s2, v0
	v_add_u32_e32 v24, 0x17ffff, v24
	v_mul_hi_i32 v25, v24, s78
	v_lshrrev_b32_e32 v36, 31, v25
	v_ashrrev_i32_e32 v25, 3, v25
	v_add_u32_e32 v36, v25, v36
	v_mul_lo_u32 v25, v36, 48
	global_load_dwordx4 v[14:17], v[32:33], off
	global_load_dword v55, v[18:19], off
	global_load_dword v56, v[18:19], off offset:8
	global_load_dword v57, v[18:19], off offset:16
	v_mad_i64_i32 v[18:19], s[4:5], v20, s92, v[22:23]
	v_lshlrev_b32_e32 v20, 6, v21
	v_sub_u32_e32 v58, v24, v25
	v_ashrrev_i32_e32 v21, 31, v20
	v_ashrrev_i32_e32 v37, 3, v58
	v_lshl_add_u64 v[18:19], v[20:21], 1, v[18:19]
	v_lshlrev_b32_e32 v59, 2, v37
	v_lshl_add_u64 v[34:35], v[18:19], 0, v[80:81]
	v_mad_i64_i32 v[24:25], s[2:3], v36, 24, s[0:1]
	v_and_b32_e32 v80, 4, v59
	v_lshl_add_u64 v[24:25], v[24:25], 0, v[80:81]
	global_load_dwordx4 v[18:21], v[34:35], off
	global_load_dword v59, v[24:25], off
	global_load_dword v60, v[24:25], off offset:8
	global_load_dword v61, v[24:25], off offset:16
	v_mad_i64_i32 v[22:23], s[2:3], v36, s92, v[22:23]
	v_lshlrev_b32_e32 v24, 6, v37
	v_and_b32_e32 v41, 7, v58
	v_ashrrev_i32_e32 v25, 31, v24
	v_cmp_gt_u32_e64 s[2:3], 16, v1
	v_and_b32_e32 v1, -16, v1
	v_lshl_add_u64 v[22:23], v[24:25], 1, v[22:23]
	v_lshlrev_b32_e32 v80, 4, v41
	v_cmp_eq_u32_e64 s[4:5], 16, v1
	v_lshl_add_u64 v[36:37], v[22:23], 0, v[80:81]
	s_waitcnt vmcnt(20)
; __device__ __forceinline__ unsigned pk2(float lo, float hi) { return cvtpk(lo, hi); }
; __device__ __forceinline__ float bflo(unsigned w) { return __uint_as_float(w << 16); }
; __device__ __forceinline__ float bfhi(unsigned w) { return __uint_as_float(w & 0xffff0000u); }
; __device__ __forceinline__ void attn_finalize(const KA& A, const Ctx& F) {
;     ...
; #pragma unroll
;         for (int u = 0; u < 6; ++u) { const int item = T * 48 - 1 - ((o * 6 + u) * (F.G * NTHREADS) + F.bid * NTHREADS + F.tid); const int g = ((item % 48) >> 4);
;             const float lm = (g == 0) ? l0[u] : (g == 1 ? l1[u] : l2[u]);
;             const float mx = fmaxf(l0[u], fmaxf(l1[u], l2[u]));
;             const float al = __expf(lm - mx) * __builtin_amdgcn_rcpf(__expf(l0[u] - mx) + __expf(l1[u] - mx) + __expf(l2[u] - mx));
;             v4u x = w[u];
;             x.x = pk2(bflo(x.x) * al, bfhi(x.x) * al); x.y = pk2(bflo(x.y) * al, bfhi(x.y) * al); x.z = pk2(bflo(x.z) * al, bfhi(x.z) * al); x.w = pk2(bflo(x.w) * al, bfhi(x.w) * al);
;             if (!(F.dry && (DRY_SEL & 4))) *p[u] = x; }
	v_max3_f32 v41, v38, v39, v40
	v_cndmask_b32_e64 v1, v40, v39, s[4:5]
	global_load_dwordx4 v[22:25], v[36:37], off
	s_waitcnt vmcnt(0)
	v_cndmask_b32_e64 v1, v1, v38, s[2:3]
	v_sub_f32_e32 v38, v38, v41
	v_sub_f32_e32 v39, v39, v41
	v_mul_f32_e32 v38, 0x3fb8aa3b, v38
	v_mul_f32_e32 v39, 0x3fb8aa3b, v39
	v_exp_f32_e32 v38, v38
	v_exp_f32_e32 v39, v39
	v_sub_f32_e32 v1, v1, v41
	v_mul_f32_e32 v1, 0x3fb8aa3b, v1
	v_exp_f32_e32 v1, v1
	v_add_f32_e32 v38, v38, v39
	v_sub_f32_e32 v39, v40, v41
	v_mul_f32_e32 v39, 0x3fb8aa3b, v39
	v_exp_f32_e32 v39, v39
	v_lshlrev_b32_e32 v40, 16, v2
	v_and_b32_e32 v41, 0xffff0000, v2
	v_cmp_gt_u32_e64 s[2:3], 16, v42
	v_add_f32_e32 v38, v39, v38
	v_rcp_f32_e32 v38, v38
	s_and_b64 vcc, exec, vcc
	v_mul_f32_e32 v38, v38, v1
	v_pk_mul_f32 v[40:41], v[38:39], v[40:41] op_sel_hi:[0,1]
	v_cvt_pk_bf16_f32 v2, v40, v41
	v_lshlrev_b32_e32 v40, 16, v3
	v_and_b32_e32 v41, 0xffff0000, v3
	v_pk_mul_f32 v[40:41], v[38:39], v[40:41] op_sel_hi:[0,1]
	v_cvt_pk_bf16_f32 v3, v40, v41
	v_lshlrev_b32_e32 v40, 16, v4
	v_and_b32_e32 v41, 0xffff0000, v4
	v_pk_mul_f32 v[40:41], v[38:39], v[40:41] op_sel_hi:[0,1]
	v_cvt_pk_bf16_f32 v4, v40, v41
	v_lshlrev_b32_e32 v40, 16, v5
	v_and_b32_e32 v41, 0xffff0000, v5
	v_pk_mul_f32 v[38:39], v[38:39], v[40:41] op_sel_hi:[0,1]
	v_and_b32_e32 v1, -16, v42
	v_cvt_pk_bf16_f32 v5, v38, v39
	v_cmp_eq_u32_e64 s[4:5], 16, v1
	global_store_dwordx4 v[26:27], v[2:5], off
	s_nop 0
	v_cndmask_b32_e64 v1, v45, v44, s[4:5]
	v_max3_f32 v2, v43, v44, v45
	v_cndmask_b32_e64 v1, v1, v43, s[2:3]
	v_sub_f32_e32 v3, v43, v2
	v_sub_f32_e32 v4, v44, v2
	v_sub_f32_e32 v1, v1, v2
	v_mul_f32_e32 v3, 0x3fb8aa3b, v3
	v_mul_f32_e32 v4, 0x3fb8aa3b, v4
	v_sub_f32_e32 v2, v45, v2
	v_exp_f32_e32 v3, v3
	v_exp_f32_e32 v4, v4
	v_mul_f32_e32 v2, 0x3fb8aa3b, v2
	v_exp_f32_e32 v2, v2
	v_mul_f32_e32 v1, 0x3fb8aa3b, v1
	v_add_f32_e32 v3, v3, v4
	v_exp_f32_e32 v1, v1
	v_add_f32_e32 v2, v2, v3
	v_rcp_f32_e32 v2, v2
	v_and_b32_e32 v3, 0xffff0000, v6
	v_lshlrev_b32_e32 v4, 16, v7
	v_and_b32_e32 v5, 0xffff0000, v7
	v_mul_f32_e32 v26, v1, v2
	v_lshlrev_b32_e32 v2, 16, v6
	v_pk_mul_f32 v[2:3], v[26:27], v[2:3] op_sel_hi:[0,1]
	v_pk_mul_f32 v[4:5], v[26:27], v[4:5] op_sel_hi:[0,1]
	v_cvt_pk_bf16_f32 v2, v2, v3
	v_cvt_pk_bf16_f32 v3, v4, v5
	v_lshlrev_b32_e32 v4, 16, v8
	v_and_b32_e32 v5, 0xffff0000, v8
	v_lshlrev_b32_e32 v6, 16, v9
	v_and_b32_e32 v7, 0xffff0000, v9
	v_pk_mul_f32 v[4:5], v[26:27], v[4:5] op_sel_hi:[0,1]
	v_pk_mul_f32 v[6:7], v[26:27], v[6:7] op_sel_hi:[0,1]
	v_and_b32_e32 v1, -16, v46
	v_cvt_pk_bf16_f32 v4, v4, v5
	v_cvt_pk_bf16_f32 v5, v6, v7
	v_cmp_eq_u32_e64 s[4:5], 16, v1
	global_store_dwordx4 v[28:29], v[2:5], off
	v_cmp_gt_u32_e64 s[2:3], 16, v46
	v_cndmask_b32_e64 v1, v49, v48, s[4:5]
	v_max3_f32 v2, v47, v48, v49
	v_cndmask_b32_e64 v1, v1, v47, s[2:3]
	v_sub_f32_e32 v3, v47, v2
	v_sub_f32_e32 v4, v48, v2
	v_sub_f32_e32 v1, v1, v2
	v_mul_f32_e32 v3, 0x3fb8aa3b, v3
	v_mul_f32_e32 v4, 0x3fb8aa3b, v4
	v_sub_f32_e32 v2, v49, v2
	v_exp_f32_e32 v3, v3
	v_exp_f32_e32 v4, v4
	v_mul_f32_e32 v2, 0x3fb8aa3b, v2
	v_exp_f32_e32 v2, v2
	v_mul_f32_e32 v1, 0x3fb8aa3b, v1
	v_add_f32_e32 v3, v3, v4
	v_exp_f32_e32 v1, v1
	v_add_f32_e32 v2, v2, v3
	v_rcp_f32_e32 v2, v2
	v_and_b32_e32 v3, 0xffff0000, v10
	v_lshlrev_b32_e32 v4, 16, v11
	v_and_b32_e32 v5, 0xffff0000, v11
	v_mul_f32_e32 v6, v1, v2
	v_lshlrev_b32_e32 v2, 16, v10
	v_pk_mul_f32 v[2:3], v[6:7], v[2:3] op_sel_hi:[0,1]
	v_pk_mul_f32 v[4:5], v[6:7], v[4:5] op_sel_hi:[0,1]
	v_cvt_pk_bf16_f32 v2, v2, v3
	v_cvt_pk_bf16_f32 v3, v4, v5
	v_lshlrev_b32_e32 v4, 16, v12
	v_and_b32_e32 v5, 0xffff0000, v12
	v_lshlrev_b32_e32 v8, 16, v13
	v_and_b32_e32 v9, 0xffff0000, v13
	v_pk_mul_f32 v[4:5], v[6:7], v[4:5] op_sel_hi:[0,1]
	v_pk_mul_f32 v[6:7], v[6:7], v[8:9] op_sel_hi:[0,1]
	v_and_b32_e32 v1, -16, v50
	v_cvt_pk_bf16_f32 v4, v4, v5
	v_cvt_pk_bf16_f32 v5, v6, v7
	v_cmp_eq_u32_e64 s[4:5], 16, v1
; __device__ __forceinline__ unsigned pk2(float lo, float hi) { return cvtpk(lo, hi); }
; __device__ __forceinline__ float bflo(unsigned w) { return __uint_as_float(w << 16); }
; __device__ __forceinline__ float bfhi(unsigned w) { return __uint_as_float(w & 0xffff0000u); }
; __device__ __forceinline__ void attn_finalize(const KA& A, const Ctx& F) {
;     ...
; #pragma unroll
;         for (int u = 0; u < 6; ++u) { const int item = T * 48 - 1 - ((o * 6 + u) * (F.G * NTHREADS) + F.bid * NTHREADS + F.tid); const int g = ((item % 48) >> 4);
;             const float lm = (g == 0) ? l0[u] : (g == 1 ? l1[u] : l2[u]);
;             const float mx = fmaxf(l0[u], fmaxf(l1[u], l2[u]));
;             const float al = __expf(lm - mx) * __builtin_amdgcn_rcpf(__expf(l0[u] - mx) + __expf(l1[u] - mx) + __expf(l2[u] - mx));
;             v4u x = w[u];
;             x.x = pk2(bflo(x.x) * al, bfhi(x.x) * al); x.y = pk2(bflo(x.y) * al, bfhi(x.y) * al); x.z = pk2(bflo(x.z) * al, bfhi(x.z) * al); x.w = pk2(bflo(x.w) * al, bfhi(x.w) * al);
;             if (!(F.dry && (DRY_SEL & 4))) *p[u] = x; }
	global_store_dwordx4 v[30:31], v[2:5], off
	v_cmp_gt_u32_e64 s[2:3], 16, v50
	v_cndmask_b32_e64 v1, v53, v52, s[4:5]
	v_max3_f32 v2, v51, v52, v53
	v_cndmask_b32_e64 v1, v1, v51, s[2:3]
	v_sub_f32_e32 v3, v51, v2
	v_sub_f32_e32 v4, v52, v2
	v_sub_f32_e32 v1, v1, v2
	v_mul_f32_e32 v3, 0x3fb8aa3b, v3
	v_mul_f32_e32 v4, 0x3fb8aa3b, v4
	v_sub_f32_e32 v2, v53, v2
	v_exp_f32_e32 v3, v3
	v_exp_f32_e32 v4, v4
	v_mul_f32_e32 v2, 0x3fb8aa3b, v2
	v_exp_f32_e32 v2, v2
	v_mul_f32_e32 v1, 0x3fb8aa3b, v1
	v_add_f32_e32 v3, v3, v4
	v_exp_f32_e32 v1, v1
	v_add_f32_e32 v2, v2, v3
	v_rcp_f32_e32 v2, v2
	v_and_b32_e32 v3, 0xffff0000, v14
	v_lshlrev_b32_e32 v4, 16, v15
	v_and_b32_e32 v5, 0xffff0000, v15
	v_mul_f32_e32 v6, v1, v2
	v_lshlrev_b32_e32 v2, 16, v14
	v_pk_mul_f32 v[2:3], v[6:7], v[2:3] op_sel_hi:[0,1]
	v_pk_mul_f32 v[4:5], v[6:7], v[4:5] op_sel_hi:[0,1]
	v_cvt_pk_bf16_f32 v2, v2, v3
	v_cvt_pk_bf16_f32 v3, v4, v5
	v_lshlrev_b32_e32 v4, 16, v16
	v_and_b32_e32 v5, 0xffff0000, v16
	v_lshlrev_b32_e32 v8, 16, v17
	v_and_b32_e32 v9, 0xffff0000, v17
	v_pk_mul_f32 v[4:5], v[6:7], v[4:5] op_sel_hi:[0,1]
	v_pk_mul_f32 v[6:7], v[6:7], v[8:9] op_sel_hi:[0,1]
	v_and_b32_e32 v1, -16, v54
	v_cvt_pk_bf16_f32 v4, v4, v5
	v_cvt_pk_bf16_f32 v5, v6, v7
	v_cmp_eq_u32_e64 s[4:5], 16, v1
	global_store_dwordx4 v[32:33], v[2:5], off
	v_cmp_gt_u32_e64 s[2:3], 16, v54
	v_cndmask_b32_e64 v1, v57, v56, s[4:5]
	v_max3_f32 v2, v55, v56, v57
	v_cndmask_b32_e64 v1, v1, v55, s[2:3]
	v_sub_f32_e32 v3, v55, v2
	v_sub_f32_e32 v4, v56, v2
	v_sub_f32_e32 v1, v1, v2
	v_mul_f32_e32 v3, 0x3fb8aa3b, v3
	v_mul_f32_e32 v4, 0x3fb8aa3b, v4
	v_sub_f32_e32 v2, v57, v2
	v_exp_f32_e32 v3, v3
	v_exp_f32_e32 v4, v4
	v_mul_f32_e32 v2, 0x3fb8aa3b, v2
	v_exp_f32_e32 v2, v2
	v_mul_f32_e32 v1, 0x3fb8aa3b, v1
	v_add_f32_e32 v3, v3, v4
	v_exp_f32_e32 v1, v1
	v_add_f32_e32 v2, v2, v3
	v_rcp_f32_e32 v2, v2
	v_and_b32_e32 v3, 0xffff0000, v18
	v_lshlrev_b32_e32 v4, 16, v19
	v_and_b32_e32 v5, 0xffff0000, v19
	v_mul_f32_e32 v6, v1, v2
	v_lshlrev_b32_e32 v2, 16, v18
	v_pk_mul_f32 v[2:3], v[6:7], v[2:3] op_sel_hi:[0,1]
	v_pk_mul_f32 v[4:5], v[6:7], v[4:5] op_sel_hi:[0,1]
	v_cvt_pk_bf16_f32 v2, v2, v3
	v_cvt_pk_bf16_f32 v3, v4, v5
	v_lshlrev_b32_e32 v4, 16, v20
	v_and_b32_e32 v5, 0xffff0000, v20
	v_lshlrev_b32_e32 v8, 16, v21
	v_and_b32_e32 v9, 0xffff0000, v21
	v_pk_mul_f32 v[4:5], v[6:7], v[4:5] op_sel_hi:[0,1]
	v_pk_mul_f32 v[6:7], v[6:7], v[8:9] op_sel_hi:[0,1]
	v_and_b32_e32 v1, -16, v58
	v_cvt_pk_bf16_f32 v4, v4, v5
	v_cvt_pk_bf16_f32 v5, v6, v7
	v_cmp_eq_u32_e64 s[4:5], 16, v1
	global_store_dwordx4 v[34:35], v[2:5], off
	v_cmp_gt_u32_e64 s[2:3], 16, v58
	v_cndmask_b32_e64 v1, v61, v60, s[4:5]
	v_max3_f32 v2, v59, v60, v61
	v_cndmask_b32_e64 v1, v1, v59, s[2:3]
	v_sub_f32_e32 v3, v59, v2
	v_sub_f32_e32 v4, v60, v2
	v_sub_f32_e32 v1, v1, v2
	v_mul_f32_e32 v3, 0x3fb8aa3b, v3
	v_mul_f32_e32 v4, 0x3fb8aa3b, v4
	v_sub_f32_e32 v2, v61, v2
	v_exp_f32_e32 v3, v3
	v_exp_f32_e32 v4, v4
	v_mul_f32_e32 v2, 0x3fb8aa3b, v2
	v_exp_f32_e32 v2, v2
	v_mul_f32_e32 v1, 0x3fb8aa3b, v1
	v_add_f32_e32 v3, v3, v4
	v_exp_f32_e32 v1, v1
	v_add_f32_e32 v2, v2, v3
	v_rcp_f32_e32 v2, v2
	v_and_b32_e32 v3, 0xffff0000, v22
	v_lshlrev_b32_e32 v4, 16, v23
	v_and_b32_e32 v5, 0xffff0000, v23
	v_mul_f32_e32 v6, v1, v2
	v_lshlrev_b32_e32 v2, 16, v22
	v_pk_mul_f32 v[2:3], v[6:7], v[2:3] op_sel_hi:[0,1]
	v_pk_mul_f32 v[4:5], v[6:7], v[4:5] op_sel_hi:[0,1]
	v_cvt_pk_bf16_f32 v2, v2, v3
	v_cvt_pk_bf16_f32 v3, v4, v5
	v_lshlrev_b32_e32 v4, 16, v24
	v_and_b32_e32 v5, 0xffff0000, v24
	v_lshlrev_b32_e32 v8, 16, v25
	v_and_b32_e32 v9, 0xffff0000, v25
	v_pk_mul_f32 v[4:5], v[6:7], v[4:5] op_sel_hi:[0,1]
	v_pk_mul_f32 v[6:7], v[6:7], v[8:9] op_sel_hi:[0,1]
	v_cvt_pk_bf16_f32 v4, v4, v5
	v_cvt_pk_bf16_f32 v5, v6, v7
	s_mov_b32 s4, 0x7ffffa
	s_mov_b64 s[2:3], 0
	global_store_dwordx4 v[36:37], v[2:5], off
	s_cbranch_vccz .LBB0_166
	s_mov_b64 s[4:5], -1

; __global__ void __launch_bounds__(NTHREADS, 2) mega_fwd(Args args) {
;     ...
;         if (ph + 1 < args.ph_hi) {
;     ...
;             for (int e_ = 0; e_ < EXTRA_SYNCS; ++e_) { XcdBarrier b2 = bar; asm volatile("" : "+s"(b2.bar)); int tb_; asm volatile("v_mbcnt_lo_u32_b32 %0, -1, 0\n\tv_mbcnt_hi_u32_b32 %0, -1, %0\n\tv_or_b32 %0, %1, %0" : "=&v"(tb_) : "s"(wv0 << 6)); xcd_barrier(b2, tb_); }
;     ...
;             if (args.ph_lo < 0) { __threadfence(); cg::this_grid().sync(); }
;             { XcdBarrier b2 = bar; asm volatile("" : "+s"(b2.bar)); int tb_; asm volatile("v_mbcnt_lo_u32_b32 %0, -1, 0\n\tv_mbcnt_hi_u32_b32 %0, -1, %0\n\tv_or_b32 %0, %1, %0" : "=&v"(tb_) : "s"(wv0 << 6)); xcd_barrier(b2, tb_); } }
.LBB0_552:
	s_andn2_saveexec_b64 s[4:5], s[4:5]
	s_cbranch_execz .LBB0_8
	s_add_i32 s4, s70, -2
	s_cmp_lt_u32 s4, 15
	s_cbranch_scc0 .Lxb_global
	s_lshr_b32 s5, 0x77ff, s4
	s_and_b32 s5, s5, 1
	s_cbranch_scc0 .Lxb_global
	v_readfirstlane_b32 s5, v18
	s_cmp_eq_u32 s5, 0
	s_cbranch_scc0 .Lxb_global
	s_mov_b64 s[0:1], exec
	s_branch .LBB0_7
